# gdn_scan step: the eight state-tile packs rotate over four VGPR pairs instead of reusing one pair right behind the store that reads it
# baseline (speedup 1.0000x reference)
.LBB0_552:
	v_cndmask_b32_e64 v103, 0, 1, s[22:23]
	v_lshl_add_u64 v[104:105], s[6:7], 0, v[100:101]
	v_cvt_pk_bf16_f32 v236, v30, v31
	v_cvt_pk_bf16_f32 v237, v32, v33
	v_cmp_ne_u32_e64 s[38:39], 1, v103
	s_andn2_b64 vcc, exec, s[22:23]
	s_mov_b64 s[16:17], -1
	ds_write_b64 v131, v[236:237]
	s_cbranch_vccnz .LBB0_554
	s_mov_b64 s[16:17], 0
	global_store_dwordx2 v[104:105], v[236:237], off
.LBB0_554:
	s_andn2_b64 vcc, exec, s[16:17]
	s_cbranch_vccnz .LBB0_556
	v_lshl_add_u64 v[146:147], s[6:7], 0, v[98:99]
	global_store_short v[146:147], v236, off
	global_store_short_d16_hi v[146:147], v236, off offset:256
	global_store_short v[146:147], v237, off offset:512
	global_store_short_d16_hi v[146:147], v237, off offset:768
.LBB0_556:
	v_cvt_pk_bf16_f32 v238, v18, v19
	v_cvt_pk_bf16_f32 v239, v20, v21
	s_and_b64 vcc, exec, s[38:39]
	s_mov_b64 s[16:17], -1
	ds_write_b64 v131, v[238:239] offset:32
	s_cbranch_vccnz .LBB0_558
	s_mov_b64 s[16:17], 0
	global_store_dwordx2 v[104:105], v[238:239], off offset:32
.LBB0_558:
	s_andn2_b64 vcc, exec, s[16:17]
	s_cbranch_vccnz .LBB0_560
	v_lshl_add_u64 v[146:147], s[6:7], 0, v[98:99]
	v_add_co_u32_e32 v146, vcc, 0x1000, v146
	s_nop 1
	v_addc_co_u32_e32 v147, vcc, 0, v147, vcc
	global_store_short v[146:147], v238, off
	global_store_short_d16_hi v[146:147], v238, off offset:256
	global_store_short v[146:147], v239, off offset:512
	global_store_short_d16_hi v[146:147], v239, off offset:768
.LBB0_560:
	v_cvt_pk_bf16_f32 v242, v10, v11
	v_cvt_pk_bf16_f32 v243, v12, v13
	s_and_b64 vcc, exec, s[38:39]
	s_mov_b64 s[16:17], -1
	ds_write_b64 v131, v[242:243] offset:64
	s_cbranch_vccnz .LBB0_562
	s_mov_b64 s[16:17], 0
	global_store_dwordx2 v[104:105], v[242:243], off offset:64
.LBB0_562:
	s_andn2_b64 vcc, exec, s[16:17]
	s_cbranch_vccnz .LBB0_564
	v_lshl_add_u64 v[146:147], s[6:7], 0, v[98:99]
	v_add_co_u32_e32 v146, vcc, 0x2000, v146
	s_nop 1
	v_addc_co_u32_e32 v147, vcc, 0, v147, vcc
	global_store_short v[146:147], v242, off
	global_store_short_d16_hi v[146:147], v242, off offset:256
	global_store_short v[146:147], v243, off offset:512
	global_store_short_d16_hi v[146:147], v243, off offset:768
.LBB0_564:
	v_cvt_pk_bf16_f32 v244, v2, v3
	v_cvt_pk_bf16_f32 v245, v4, v5
	s_and_b64 vcc, exec, s[38:39]
	s_mov_b64 s[16:17], -1
	ds_write_b64 v131, v[244:245] offset:96
	s_cbranch_vccnz .LBB0_566
	s_mov_b64 s[16:17], 0
	global_store_dwordx2 v[104:105], v[244:245], off offset:96
.LBB0_566:
	s_andn2_b64 vcc, exec, s[16:17]
	s_cbranch_vccnz .LBB0_568
	v_lshl_add_u64 v[146:147], s[6:7], 0, v[98:99]
	v_add_co_u32_e32 v146, vcc, 0x3000, v146
	s_nop 1
	v_addc_co_u32_e32 v147, vcc, 0, v147, vcc
	global_store_short v[146:147], v244, off
	global_store_short_d16_hi v[146:147], v244, off offset:256
	global_store_short v[146:147], v245, off offset:512
	global_store_short_d16_hi v[146:147], v245, off offset:768
.LBB0_568:
	v_cvt_pk_bf16_f32 v236, v6, v7
	v_cvt_pk_bf16_f32 v237, v8, v9
	s_and_b64 vcc, exec, s[38:39]
	s_mov_b64 s[16:17], -1
	ds_write_b64 v131, v[236:237] offset:128
	s_cbranch_vccnz .LBB0_570
	s_mov_b64 s[16:17], 0
	global_store_dwordx2 v[104:105], v[236:237], off offset:128
.LBB0_570:
	s_andn2_b64 vcc, exec, s[16:17]
	s_cbranch_vccnz .LBB0_572
	v_lshl_add_u64 v[146:147], s[6:7], 0, v[98:99]
	v_add_co_u32_e32 v146, vcc, 0x4000, v146
	s_nop 1
	v_addc_co_u32_e32 v147, vcc, 0, v147, vcc
	global_store_short v[146:147], v236, off
	global_store_short_d16_hi v[146:147], v236, off offset:256
	global_store_short v[146:147], v237, off offset:512
	global_store_short_d16_hi v[146:147], v237, off offset:768
.LBB0_572:
	v_cvt_pk_bf16_f32 v238, v14, v15
	v_cvt_pk_bf16_f32 v239, v16, v17
	s_and_b64 vcc, exec, s[38:39]
	s_mov_b64 s[16:17], -1
	ds_write_b64 v131, v[238:239] offset:160
	s_cbranch_vccnz .LBB0_574
	s_mov_b64 s[16:17], 0
	global_store_dwordx2 v[104:105], v[238:239], off offset:160
.LBB0_574:
	s_andn2_b64 vcc, exec, s[16:17]
	s_cbranch_vccnz .LBB0_576
	v_lshl_add_u64 v[146:147], s[6:7], 0, v[98:99]
	v_add_co_u32_e32 v146, vcc, 0x5000, v146
	s_nop 1
	v_addc_co_u32_e32 v147, vcc, 0, v147, vcc
	global_store_short v[146:147], v238, off
	global_store_short_d16_hi v[146:147], v238, off offset:256
	global_store_short v[146:147], v239, off offset:512
	global_store_short_d16_hi v[146:147], v239, off offset:768
.LBB0_576:
	v_cvt_pk_bf16_f32 v242, v22, v23
	v_cvt_pk_bf16_f32 v243, v24, v25
	s_and_b64 vcc, exec, s[38:39]
	s_mov_b64 s[16:17], -1
	ds_write_b64 v131, v[242:243] offset:192
	s_cbranch_vccnz .LBB0_578
	s_mov_b64 s[16:17], 0
	global_store_dwordx2 v[104:105], v[242:243], off offset:192
.LBB0_578:
	s_andn2_b64 vcc, exec, s[16:17]
	s_cbranch_vccnz .LBB0_580
	v_lshl_add_u64 v[146:147], s[6:7], 0, v[98:99]
	v_add_co_u32_e32 v146, vcc, 0x6000, v146
	s_nop 1
	v_addc_co_u32_e32 v147, vcc, 0, v147, vcc
	global_store_short v[146:147], v242, off
	global_store_short_d16_hi v[146:147], v242, off offset:256
	global_store_short v[146:147], v243, off offset:512
	global_store_short_d16_hi v[146:147], v243, off offset:768
.LBB0_580:
	v_cvt_pk_bf16_f32 v244, v26, v27
	v_cvt_pk_bf16_f32 v245, v28, v29
	s_and_b64 vcc, exec, s[38:39]
	s_mov_b64 s[16:17], -1
	ds_write_b64 v131, v[244:245] offset:224
	s_cbranch_vccnz .LBB0_582
	s_mov_b64 s[16:17], 0
	global_store_dwordx2 v[104:105], v[244:245], off offset:224
.LBB0_582:
	s_andn2_b64 vcc, exec, s[16:17]
	s_cbranch_vccnz .LBB0_584
	v_lshl_add_u64 v[146:147], s[6:7], 0, v[98:99]
	v_add_co_u32_e32 v146, vcc, 0x7000, v146
	s_nop 1
	v_addc_co_u32_e32 v147, vcc, 0, v147, vcc
	global_store_short v[146:147], v244, off
	global_store_short_d16_hi v[146:147], v244, off offset:256
	global_store_short v[146:147], v245, off offset:512
	global_store_short_d16_hi v[146:147], v245, off offset:768

.LBB0_586:
	s_waitcnt lgkmcnt(0)
	s_barrier
	v_cvt_pk_bf16_f32 v236, v30, v31
	v_cvt_pk_bf16_f32 v237, v32, v33
	s_and_b64 vcc, exec, s[38:39]
	s_mov_b64 s[16:17], -1
	ds_write_b64 v131, v[236:237]
	s_cbranch_vccnz .LBB0_588
	v_add_co_u32_e32 v148, vcc, 0x20000, v104
	s_mov_b64 s[16:17], 0
	s_nop 0
	v_addc_co_u32_e32 v149, vcc, 0, v105, vcc
	global_store_dwordx2 v[148:149], v[236:237], off
.LBB0_588:
	s_andn2_b64 vcc, exec, s[16:17]
	s_cbranch_vccnz .LBB0_590
	v_lshl_add_u64 v[148:149], s[6:7], 0, v[98:99]
	v_add_co_u32_e32 v148, vcc, 0x20000, v148
	s_nop 1
	v_addc_co_u32_e32 v149, vcc, 0, v149, vcc
	global_store_short v[148:149], v236, off
	global_store_short_d16_hi v[148:149], v236, off offset:256
	global_store_short v[148:149], v237, off offset:512
	global_store_short_d16_hi v[148:149], v237, off offset:768
.LBB0_590:
	v_cvt_pk_bf16_f32 v238, v18, v19
	v_cvt_pk_bf16_f32 v239, v20, v21
	s_and_b64 vcc, exec, s[38:39]
	s_mov_b64 s[16:17], -1
	ds_write_b64 v131, v[238:239] offset:32
	s_cbranch_vccnz .LBB0_592
	v_add_co_u32_e32 v148, vcc, 0x20000, v104
	s_mov_b64 s[16:17], 0
	s_nop 0
	v_addc_co_u32_e32 v149, vcc, 0, v105, vcc
	global_store_dwordx2 v[148:149], v[238:239], off offset:32
.LBB0_592:
	s_andn2_b64 vcc, exec, s[16:17]
	s_cbranch_vccnz .LBB0_594
	v_lshl_add_u64 v[148:149], s[6:7], 0, v[98:99]
	v_add_co_u32_e32 v148, vcc, 0x21000, v148
	s_nop 1
	v_addc_co_u32_e32 v149, vcc, 0, v149, vcc
	global_store_short v[148:149], v238, off
	global_store_short_d16_hi v[148:149], v238, off offset:256
	global_store_short v[148:149], v239, off offset:512
	global_store_short_d16_hi v[148:149], v239, off offset:768
.LBB0_594:
	v_cvt_pk_bf16_f32 v242, v10, v11
	v_cvt_pk_bf16_f32 v243, v12, v13
	s_and_b64 vcc, exec, s[38:39]
	s_mov_b64 s[16:17], -1
	ds_write_b64 v131, v[242:243] offset:64
	s_cbranch_vccnz .LBB0_596
	v_add_co_u32_e32 v148, vcc, 0x20000, v104
	s_mov_b64 s[16:17], 0
	s_nop 0
	v_addc_co_u32_e32 v149, vcc, 0, v105, vcc
	global_store_dwordx2 v[148:149], v[242:243], off offset:64
.LBB0_596:
	s_andn2_b64 vcc, exec, s[16:17]
	s_cbranch_vccnz .LBB0_598
	v_lshl_add_u64 v[148:149], s[6:7], 0, v[98:99]
	v_add_co_u32_e32 v148, vcc, 0x22000, v148
	s_nop 1
	v_addc_co_u32_e32 v149, vcc, 0, v149, vcc
	global_store_short v[148:149], v242, off
	global_store_short_d16_hi v[148:149], v242, off offset:256
	global_store_short v[148:149], v243, off offset:512
	global_store_short_d16_hi v[148:149], v243, off offset:768
.LBB0_598:
	v_cvt_pk_bf16_f32 v244, v2, v3
	v_cvt_pk_bf16_f32 v245, v4, v5
	s_and_b64 vcc, exec, s[38:39]
	s_mov_b64 s[16:17], -1
	ds_write_b64 v131, v[244:245] offset:96
	s_cbranch_vccnz .LBB0_600
	v_add_co_u32_e32 v148, vcc, 0x20000, v104
	s_mov_b64 s[16:17], 0
	s_nop 0
	v_addc_co_u32_e32 v149, vcc, 0, v105, vcc
	global_store_dwordx2 v[148:149], v[244:245], off offset:96
.LBB0_600:
	s_andn2_b64 vcc, exec, s[16:17]
	s_cbranch_vccnz .LBB0_602
	v_lshl_add_u64 v[148:149], s[6:7], 0, v[98:99]
	v_add_co_u32_e32 v148, vcc, 0x23000, v148
	s_nop 1
	v_addc_co_u32_e32 v149, vcc, 0, v149, vcc
	global_store_short v[148:149], v244, off
	global_store_short_d16_hi v[148:149], v244, off offset:256
	global_store_short v[148:149], v245, off offset:512
	global_store_short_d16_hi v[148:149], v245, off offset:768
.LBB0_602:
	v_cvt_pk_bf16_f32 v236, v6, v7
	v_cvt_pk_bf16_f32 v237, v8, v9
	s_and_b64 vcc, exec, s[38:39]
	s_mov_b64 s[16:17], -1
	ds_write_b64 v131, v[236:237] offset:128
	s_cbranch_vccnz .LBB0_604
	v_add_co_u32_e32 v148, vcc, 0x20000, v104
	s_mov_b64 s[16:17], 0
	s_nop 0
	v_addc_co_u32_e32 v149, vcc, 0, v105, vcc
	global_store_dwordx2 v[148:149], v[236:237], off offset:128
.LBB0_604:
	s_andn2_b64 vcc, exec, s[16:17]
	s_cbranch_vccnz .LBB0_606
	v_lshl_add_u64 v[148:149], s[6:7], 0, v[98:99]
	v_add_co_u32_e32 v148, vcc, 0x24000, v148
	s_nop 1
	v_addc_co_u32_e32 v149, vcc, 0, v149, vcc
	global_store_short v[148:149], v236, off
	global_store_short_d16_hi v[148:149], v236, off offset:256
	global_store_short v[148:149], v237, off offset:512
	global_store_short_d16_hi v[148:149], v237, off offset:768
.LBB0_606:
	v_cvt_pk_bf16_f32 v238, v14, v15
	v_cvt_pk_bf16_f32 v239, v16, v17
	s_and_b64 vcc, exec, s[38:39]
	s_mov_b64 s[16:17], -1
	ds_write_b64 v131, v[238:239] offset:160
	s_cbranch_vccnz .LBB0_608
	v_add_co_u32_e32 v148, vcc, 0x20000, v104
	s_mov_b64 s[16:17], 0
	s_nop 0
	v_addc_co_u32_e32 v149, vcc, 0, v105, vcc
	global_store_dwordx2 v[148:149], v[238:239], off offset:160
.LBB0_608:
	s_andn2_b64 vcc, exec, s[16:17]
	s_cbranch_vccnz .LBB0_610
	v_lshl_add_u64 v[148:149], s[6:7], 0, v[98:99]
	v_add_co_u32_e32 v148, vcc, 0x25000, v148
	s_nop 1
	v_addc_co_u32_e32 v149, vcc, 0, v149, vcc
	global_store_short v[148:149], v238, off
	global_store_short_d16_hi v[148:149], v238, off offset:256
	global_store_short v[148:149], v239, off offset:512
	global_store_short_d16_hi v[148:149], v239, off offset:768
.LBB0_610:
	v_cvt_pk_bf16_f32 v242, v22, v23
	v_cvt_pk_bf16_f32 v243, v24, v25
	s_and_b64 vcc, exec, s[38:39]
	s_mov_b64 s[16:17], -1
	ds_write_b64 v131, v[242:243] offset:192
	s_cbranch_vccnz .LBB0_612
	v_add_co_u32_e32 v148, vcc, 0x20000, v104
	s_mov_b64 s[16:17], 0
	s_nop 0
	v_addc_co_u32_e32 v149, vcc, 0, v105, vcc
	global_store_dwordx2 v[148:149], v[242:243], off offset:192
.LBB0_612:
	s_andn2_b64 vcc, exec, s[16:17]
	s_cbranch_vccnz .LBB0_614
	v_lshl_add_u64 v[148:149], s[6:7], 0, v[98:99]
	v_add_co_u32_e32 v148, vcc, 0x26000, v148
	s_nop 1
	v_addc_co_u32_e32 v149, vcc, 0, v149, vcc
	global_store_short v[148:149], v242, off
	global_store_short_d16_hi v[148:149], v242, off offset:256
	global_store_short v[148:149], v243, off offset:512
	global_store_short_d16_hi v[148:149], v243, off offset:768
.LBB0_614:
	v_cvt_pk_bf16_f32 v244, v26, v27
	v_cvt_pk_bf16_f32 v245, v28, v29
	s_and_b64 vcc, exec, s[38:39]
	s_mov_b64 s[16:17], -1
	ds_write_b64 v131, v[244:245] offset:224
	s_cbranch_vccnz .LBB0_616
	v_add_co_u32_e32 v104, vcc, 0x20000, v104
	s_mov_b64 s[16:17], 0
	s_nop 0
	v_addc_co_u32_e32 v105, vcc, 0, v105, vcc
	global_store_dwordx2 v[104:105], v[244:245], off offset:224
.LBB0_616:
	s_andn2_b64 vcc, exec, s[16:17]
	s_cbranch_vccnz .LBB0_618
	v_lshl_add_u64 v[104:105], s[6:7], 0, v[98:99]
	v_add_co_u32_e32 v104, vcc, 0x27000, v104
	s_nop 1
	v_addc_co_u32_e32 v105, vcc, 0, v105, vcc
	global_store_short v[104:105], v244, off
	global_store_short_d16_hi v[104:105], v244, off offset:256
	global_store_short v[104:105], v245, off offset:512
	global_store_short_d16_hi v[104:105], v245, off offset:768
